# strategy 4: static s_setprio 1 for waves 4-7 during the attention queue phase
# baseline (speedup 1.0000x reference)
.LBB0_314:
	v_writelane_b32 v251, s96, 45
	s_nop 1
	v_writelane_b32 v251, s97, 46
	v_writelane_b32 v251, s94, 47
	s_nop 1
	v_writelane_b32 v251, s95, 48
	v_writelane_b32 v251, s92, 49
	s_nop 1
	v_writelane_b32 v251, s93, 50
	v_writelane_b32 v251, s89, 51
	v_writelane_b32 v251, s76, 52
	v_writelane_b32 v251, s90, 53
	s_nop 1
	v_writelane_b32 v251, s91, 54
	v_writelane_b32 v251, s82, 55
	s_nop 1
	v_writelane_b32 v251, s83, 56
	v_writelane_b32 v251, s84, 57
	s_nop 1
	v_writelane_b32 v251, s85, 58
	v_writelane_b32 v251, s86, 59
	v_writelane_b32 v251, s87, 60
	s_or_b64 exec, exec, s[0:1]
	s_add_u32 s33, s34, 0x4000000
	s_addc_u32 s76, s35, 0
	s_add_u32 s60, s34, 0x6000000
	s_addc_u32 s61, s35, 0
	s_and_b32 s38, s77, 7
	s_add_u32 s77, s34, 0x4000400
	s_addc_u32 s12, s35, 0
	s_add_u32 s13, s34, 0x6000400
	s_addc_u32 s18, s35, 0
	s_add_u32 s19, s34, 0xa000000
	s_addc_u32 s20, s35, 0
	s_add_u32 s21, s34, 0xd000000
	s_addc_u32 s22, s35, 0
	s_add_u32 s23, s34, 0x2000400
	s_addc_u32 s24, s35, 0
	s_add_u32 s56, s34, 0x8000000
	s_addc_u32 s57, s35, 0
	s_add_u32 s25, s34, 0x2000
	s_addc_u32 s82, s35, 0
	s_add_i32 s0, s88, 1
	s_lshl_b32 s1, s0, 8
	s_and_b32 s1, s1, 0x700
	s_add_u32 s4, s25, s1
	s_addc_u32 s5, s82, 0
	v_writelane_b32 v251, s4, 61
	s_add_i32 s1, s88, 2
	s_mov_b32 s86, 2.0
	v_writelane_b32 v251, s5, 62
	s_lshl_b32 s4, s1, 8
	s_and_b32 s4, s4, 0x700
	s_add_u32 s4, s25, s4
	s_addc_u32 s5, s82, 0
	v_writelane_b32 v251, s4, 63
	s_mov_b32 s90, 0x41200000
	s_mov_b32 s92, 0x41800000
	v_writelane_b32 v250, s5, 0
	s_add_i32 s4, s88, 3
	s_lshl_b32 s5, s4, 8
	s_and_b32 s5, s5, 0x700
	s_add_u32 s6, s25, s5
	s_addc_u32 s7, s82, 0
	v_writelane_b32 v250, s6, 1
	s_add_i32 s5, s88, 4
	s_mov_b32 s94, 0x41900000
	v_writelane_b32 v250, s7, 2
	s_lshl_b32 s6, s5, 8
	s_and_b32 s6, s6, 0x700
	s_add_u32 s6, s25, s6
	s_addc_u32 s7, s82, 0
	v_writelane_b32 v250, s6, 3
	s_mov_b32 s96, 0x41c00000
	s_mov_b32 s80, 0xfffe0000
	v_writelane_b32 v250, s7, 4
	s_add_i32 s6, s88, 5
	s_lshl_b32 s7, s6, 8
	s_and_b32 s7, s7, 0x700
	s_add_u32 s16, s25, s7
	s_addc_u32 s17, s82, 0
	s_add_i32 s7, s88, 6
	s_lshl_b32 s10, s7, 8
	v_writelane_b32 v250, s16, 5
	s_and_b32 s10, s10, 0x700
	s_mov_b32 s11, 0
	v_writelane_b32 v250, s17, 6
	s_add_u32 s16, s25, s10
	s_addc_u32 s17, s82, 0
	v_writelane_b32 v250, s16, 7
	s_add_i32 s10, s88, 7
	v_mov_b32_e32 v207, 0
	v_writelane_b32 v250, s17, 8
	s_lshl_b32 s16, s10, 8
	s_and_b32 s16, s16, 0x700
	s_add_u32 s16, s25, s16
	v_writelane_b32 v250, s88, 9
	s_addc_u32 s17, s82, 0
	v_writelane_b32 v250, s16, 10
	s_and_b32 s10, s10, 7
	s_and_b32 s7, s7, 7
	v_writelane_b32 v250, s17, 11
	v_writelane_b32 v250, s10, 12
	v_writelane_b32 v250, s7, 13
	s_and_b32 s6, s6, 7
	v_writelane_b32 v250, s6, 14
	s_and_b32 s5, s5, 7
	v_writelane_b32 v250, s5, 15
	s_and_b32 s4, s4, 7
	v_writelane_b32 v250, s4, 16
	s_and_b32 s1, s1, 7
	v_writelane_b32 v250, s1, 17
	s_and_b32 s0, s0, 7
	s_mov_b32 s88, 0x41000000
	s_mov_b32 s16, 0x41d00000
	v_writelane_b32 v250, s0, 18
	v_or_b32_e32 v232, 64, v202
	v_cmp_gt_u32_e64 s[4:5], 4, v202
	v_and_b32_e32 v233, 3, v0
	s_mov_b64 s[0:1], -1
	s_movk_i32 s83, 0x140
	s_add_i32 s84, 0, 0x22180
	s_movk_i32 s85, 0x13f
	s_movk_i32 s26, 0x81
	s_mov_b32 s87, 0x40400000
	s_mov_b32 s89, 0x41100000
	s_mov_b32 s91, 0x41300000
	s_mov_b32 s93, 0x41880000
	s_mov_b32 s95, 0x41980000
	s_mov_b32 s97, 0x41c80000
	s_mov_b32 s17, 0x41d80000
	s_mov_b32 s27, 0xf800000
	v_mov_b32_e32 v234, 0x260
	v_mov_b32_e32 v208, 0x3c23d70a
	s_mov_b64 s[78:79], 0x20000
	s_mov_b64 s[62:63], 0x40000
	s_mov_b64 s[74:75], 0x60000
	s_mov_b32 s81, -1
	v_mov_b32_e32 v235, 0xff800000
	v_mbcnt_hi_u32_b32 v231, -1, v1
	v_mov_b32_e32 v1, 0x42800000
	s_mov_b32 s10, 0
	v_mov_b32_e32 v236, 0
	s_waitcnt lgkmcnt(0)
	s_barrier
	v_readfirstlane_b32 s100, v0
	s_lshr_b32 s100, s100, 8
	s_cmp_eq_u32 s100, 0
	s_cbranch_scc1 .Lprio_skip
	s_setprio 1
.Lprio_skip:
	s_branch .LBB0_317
.LBB0_315:
	s_mov_b64 s[6:7], 0

.LBB0_441:
	s_setprio 0
	s_waitcnt vmcnt(0)
	s_barrier
	s_and_saveexec_b64 s[0:1], s[14:15]
	v_readlane_b32 s92, v251, 57
	v_readlane_b32 s96, v251, 55
	v_readlane_b32 s84, v251, 6
	v_readlane_b32 s93, v251, 58
	v_readlane_b32 s94, v251, 59
	v_readlane_b32 s95, v251, 60
	v_readlane_b32 s97, v251, 56
	v_readlane_b32 s90, v250, 9
	v_readlane_b32 s89, v251, 52
	v_readlane_b32 s85, v251, 7
	s_cbranch_execz .LBB0_493
	s_add_i32 s4, 0, 0x22160
	v_mov_b32_e32 v1, s4
	s_waitcnt vmcnt(0) expcnt(0) lgkmcnt(0)
	ds_read_b32 v3, v1
	s_add_i32 s4, 0, 0x22164
	v_mov_b32_e32 v1, s4
	ds_read_b32 v1, v1
	s_waitcnt lgkmcnt(1)
	v_cmp_ne_u32_e32 vcc, 0, v3
	s_cbranch_vccnz .LBB0_457
	v_readlane_b32 s6, v251, 53
	v_readlane_b32 s7, v251, 54
	s_load_dwordx2 s[4:5], s[6:7], 0x4
	s_mov_b32 s26, 1
	v_mov_b32_e32 v17, 0
	s_waitcnt lgkmcnt(0)
	s_mul_i32 s4, s4, s5
	s_lshl_b32 s27, s4, 8
	s_add_u32 s4, s34, 0x4200
	s_addc_u32 s5, s35, 0
	s_add_u32 s6, s34, 0x4400
	s_addc_u32 s7, s35, 0
	s_add_u32 s8, s34, 0x4500
	s_addc_u32 s9, s35, 0
	s_add_u32 s10, s34, 0x4600
	s_addc_u32 s11, s35, 0
	s_add_u32 s12, s34, 0x4700
	s_addc_u32 s13, s35, 0
	s_add_u32 s16, s34, 0x4800
	s_addc_u32 s17, s35, 0
	s_add_u32 s18, s34, 0x4900
	s_addc_u32 s19, s35, 0
	s_add_u32 s20, s34, 0x4a00
	s_addc_u32 s21, s35, 0
	s_add_u32 s22, s34, 0x4b00
	s_addc_u32 s23, s35, 0
	s_add_u32 s24, s34, 0x4c00
	s_addc_u32 s25, s35, 0
	s_add_u32 s28, s34, 0x4d00
	s_addc_u32 s29, s35, 0
	s_add_u32 s30, s34, 0x4e00
	s_addc_u32 s31, s35, 0
	s_add_u32 s52, s34, 0x4f00
	s_addc_u32 s53, s35, 0
	s_add_u32 s54, s34, 0x5000
	s_addc_u32 s55, s35, 0
	s_add_u32 s62, s34, 0x5100
	s_addc_u32 s63, s35, 0
	s_add_u32 s64, s34, 0x5200
	s_addc_u32 s65, s35, 0
	s_add_u32 s66, s34, 0x5300
	s_addc_u32 s67, s35, 0
	s_branch .LBB0_445

	.amdhsa_kernel _Z6mk_fwd4Args
		.amdhsa_group_segment_fixed_size 0
		.amdhsa_private_segment_fixed_size 0
		.amdhsa_kernarg_size 408
		.amdhsa_user_sgpr_count 2
		.amdhsa_user_sgpr_dispatch_ptr 0
		.amdhsa_user_sgpr_queue_ptr 0
		.amdhsa_user_sgpr_kernarg_segment_ptr 1
		.amdhsa_user_sgpr_dispatch_id 0
		.amdhsa_user_sgpr_kernarg_preload_length 0
		.amdhsa_user_sgpr_kernarg_preload_offset 0
		.amdhsa_user_sgpr_private_segment_size 0
		.amdhsa_uses_dynamic_stack 0
		.amdhsa_enable_private_segment 0
		.amdhsa_system_sgpr_workgroup_id_x 1
		.amdhsa_system_sgpr_workgroup_id_y 0
		.amdhsa_system_sgpr_workgroup_id_z 0
		.amdhsa_system_sgpr_workgroup_info 0
		.amdhsa_system_vgpr_workitem_id 0
		.amdhsa_next_free_vgpr 256
		.amdhsa_next_free_sgpr 102
		.amdhsa_accum_offset 256
		.amdhsa_reserve_vcc 1
		.amdhsa_float_round_mode_32 0
		.amdhsa_float_round_mode_16_64 0
		.amdhsa_float_denorm_mode_32 3
		.amdhsa_float_denorm_mode_16_64 3
		.amdhsa_dx10_clamp 1
		.amdhsa_ieee_mode 1
		.amdhsa_fp16_overflow 0
		.amdhsa_tg_split 0
		.amdhsa_exception_fp_ieee_invalid_op 0
		.amdhsa_exception_fp_denorm_src 0
		.amdhsa_exception_fp_ieee_div_zero 0
		.amdhsa_exception_fp_ieee_overflow 0
		.amdhsa_exception_fp_ieee_underflow 0
		.amdhsa_exception_fp_ieee_inexact 0
		.amdhsa_exception_int_div_zero 0
	.end_amdhsa_kernel

amdhsa.kernels:
  - .agpr_count:     0
    .args:
      - .offset:         0
        .size:           152
        .value_kind:     by_value
      - .offset:         152
        .size:           4
        .value_kind:     hidden_block_count_x
      - .offset:         156
        .size:           4
        .value_kind:     hidden_block_count_y
      - .offset:         160
        .size:           4
        .value_kind:     hidden_block_count_z
      - .offset:         164
        .size:           2
        .value_kind:     hidden_group_size_x
      - .offset:         166
        .size:           2
        .value_kind:     hidden_group_size_y
      - .offset:         168
        .size:           2
        .value_kind:     hidden_group_size_z
      - .offset:         170
        .size:           2
        .value_kind:     hidden_remainder_x
      - .offset:         172
        .size:           2
        .value_kind:     hidden_remainder_y
      - .offset:         174
        .size:           2
        .value_kind:     hidden_remainder_z
      - .offset:         192
        .size:           8
        .value_kind:     hidden_global_offset_x
      - .offset:         200
        .size:           8
        .value_kind:     hidden_global_offset_y
      - .offset:         208
        .size:           8
        .value_kind:     hidden_global_offset_z
      - .offset:         216
        .size:           2
        .value_kind:     hidden_grid_dims
      - .offset:         272
        .size:           4
        .value_kind:     hidden_dynamic_lds_size
    .group_segment_fixed_size: 0
    .kernarg_segment_align: 8
    .kernarg_segment_size: 408
    .language:       OpenCL C
    .language_version:
      - 2
      - 0
    .max_flat_workgroup_size: 512
    .name:           _Z6mk_fwd4Args
    .private_segment_fixed_size: 0
    .sgpr_count:     108
    .sgpr_spill_count: 87
    .symbol:         _Z6mk_fwd4Args.kd
    .uniform_work_group_size: 1
    .uses_dynamic_stack: false
    .vgpr_count:     256
    .vgpr_spill_count: 0
    .wavefront_size: 64
